# early in-proj weight conversion (first 4480 tiles, phase 3 idle workgroups) with non-temporal loads/stores so it does not disturb the concurrent compress GEMM
# speedup vs baseline: 1.0022x; 1.0022x over previous
; __device__ __forceinline__ void tconv_tile(LAS float* tile, const float* src, int ld, int k0, int n0, int mode, bf16_t* dst, int K) {
;     ...
;     for (int it = 0; it < 2; ++it) { const int idx = tid + it * 512, kk = idx >> 4, n4 = (idx & 15) * 4, nn = n0 + n4; int oc = nn; bool valid = true;
;         if (mode == 1) { if (nn < 7680) oc = nn; else if (nn < 18944) oc = nn + 48; else if (nn < INW) oc = 7680 + (nn - 18944); else valid = false; }
;         f32x4 v = (f32x4){0.f, 0.f, 0.f, 0.f}; if (valid) v = *(const f32x4*)(src + (size_t)(k0 + kk) * ld + oc);
; __device__ __forceinline__ void prologue(LAS unsigned char* lds, const Ctx& P, int l) {
;     ...
;     for (int t = blockIdx.x; t < T_ALL; t += G) {
;         int q = t;
;         if (q < T_IN) { const int kt = q & 31, ntl = q >> 5; tconv_tile(tile, P.in[3] + (size_t)l * DM * INW, INW, kt * 64, ntl * 64, 1, (bf16_t*)(ws + WS_WIN), DM); continue; }
.Ltc2_d1:
	v_mov_b32_e32 v34, 0
	v_mov_b32_e32 v35, 0
	v_mov_b32_e32 v36, 0
	v_mov_b32_e32 v37, 0
	v_mov_b32_e32 v38, 0
	v_mov_b32_e32 v39, 0
	v_mov_b32_e32 v40, 0
	v_mov_b32_e32 v41, 0
	v_mul_u32_u24_e32 v26, s28, v20
	v_add_lshl_u32 v26, v26, v21, 2
	s_lshl_b32 s0, s28, 7
	v_add_u32_e32 v27, s0, v26
	v_cmp_gt_i32_e32 vcc, s29, v21
	s_and_saveexec_b64 s[0:1], vcc
	global_load_dwordx4 v[34:37], v26, s[26:27] nt
	global_load_dwordx4 v[38:41], v27, s[26:27] nt
	s_mov_b64 exec, s[0:1]
	s_add_u32 s24, s24, 0xe0
	s_min_u32 s0, s24, 4479
	s_mov_b32 s21, s0
	s_mov_b32 s0, s21
	s_cmpk_lt_u32 s0, 9600
	s_cbranch_scc0 .Ltc2_c15
	s_and_b32 s1, s0, 31
	s_lshl_b32 s1, s1, 6
	s_lshr_b32 s21, s0, 5
	s_lshl_b32 s21, s21, 6
	s_movk_i32 s29, 64
	s_cmpk_lt_u32 s21, 7680
	s_cbranch_scc1 .Ltc2_n17
	s_cmpk_lt_u32 s21, 18944
	s_cbranch_scc0 .Ltc2_t16
	s_add_u32 s21, s21, 48
	s_branch .Ltc2_n17

; __device__ __forceinline__ void tconv_tile(LAS float* tile, const float* src, int ld, int k0, int n0, int mode, bf16_t* dst, int K) {
;     ...
;     for (int it = 0; it < 2; ++it) { const int idx = tid + it * 512, kk = idx >> 4, n4 = (idx & 15) * 4, nn = n0 + n4; int oc = nn; bool valid = true;
;         if (mode == 1) { if (nn < 7680) oc = nn; else if (nn < 18944) oc = nn + 48; else if (nn < INW) oc = 7680 + (nn - 18944); else valid = false; }
;         f32x4 v = (f32x4){0.f, 0.f, 0.f, 0.f}; if (valid) v = *(const f32x4*)(src + (size_t)(k0 + kk) * ld + oc);
; __device__ __forceinline__ void prologue(LAS unsigned char* lds, const Ctx& P, int l) {
;     ...
;     for (int t = blockIdx.x; t < T_ALL; t += G) {
;         int q = t;
;         if (q < T_IN) { const int kt = q & 31, ntl = q >> 5; tconv_tile(tile, P.in[3] + (size_t)l * DM * INW, INW, kt * 64, ntl * 64, 1, (bf16_t*)(ws + WS_WIN), DM); continue; }
.Ltc2_d14:
	v_mov_b32_e32 v42, 0
	v_mov_b32_e32 v43, 0
	v_mov_b32_e32 v44, 0
	v_mov_b32_e32 v45, 0
	v_mov_b32_e32 v46, 0
	v_mov_b32_e32 v47, 0
	v_mov_b32_e32 v48, 0
	v_mov_b32_e32 v49, 0
	v_mul_u32_u24_e32 v26, s28, v20
	v_add_lshl_u32 v26, v26, v21, 2
	s_lshl_b32 s0, s28, 7
	v_add_u32_e32 v27, s0, v26
	v_cmp_gt_i32_e32 vcc, s29, v21
	s_and_saveexec_b64 s[0:1], vcc
	global_load_dwordx4 v[42:45], v26, s[26:27] nt
	global_load_dwordx4 v[46:49], v27, s[26:27] nt
	s_mov_b64 exec, s[0:1]
	s_add_u32 s24, s24, 0xe0
	s_min_u32 s0, s24, 4479
	s_mov_b32 s21, s0
	s_mov_b32 s0, s21
	s_cmpk_lt_u32 s0, 9600
	s_cbranch_scc0 .Ltc2_c28
	s_and_b32 s1, s0, 31
	s_lshl_b32 s1, s1, 6
	s_lshr_b32 s21, s0, 5
	s_lshl_b32 s21, s21, 6
	s_movk_i32 s29, 64
	s_cmpk_lt_u32 s21, 7680
	s_cbranch_scc1 .Ltc2_n30
	s_cmpk_lt_u32 s21, 18944
	s_cbranch_scc0 .Ltc2_t29
	s_add_u32 s21, s21, 48
	s_branch .Ltc2_n30

; __device__ __forceinline__ void tconv_tile(LAS float* tile, const float* src, int ld, int k0, int n0, int mode, bf16_t* dst, int K) {
;     ...
;     for (int it = 0; it < 2; ++it) { const int idx = tid + it * 512, kk = idx >> 4, n4 = (idx & 15) * 4, nn = n0 + n4; int oc = nn; bool valid = true;
;         if (mode == 1) { if (nn < 7680) oc = nn; else if (nn < 18944) oc = nn + 48; else if (nn < INW) oc = 7680 + (nn - 18944); else valid = false; }
;         f32x4 v = (f32x4){0.f, 0.f, 0.f, 0.f}; if (valid) v = *(const f32x4*)(src + (size_t)(k0 + kk) * ld + oc);
; __device__ __forceinline__ void prologue(LAS unsigned char* lds, const Ctx& P, int l) {
;     ...
;     for (int t = blockIdx.x; t < T_ALL; t += G) {
;         int q = t;
;         if (q < T_IN) { const int kt = q & 31, ntl = q >> 5; tconv_tile(tile, P.in[3] + (size_t)l * DM * INW, INW, kt * 64, ntl * 64, 1, (bf16_t*)(ws + WS_WIN), DM); continue; }
.Ltc2_d27:
	v_mov_b32_e32 v50, 0
	v_mov_b32_e32 v51, 0
	v_mov_b32_e32 v52, 0
	v_mov_b32_e32 v53, 0
	v_mov_b32_e32 v54, 0
	v_mov_b32_e32 v55, 0
	v_mov_b32_e32 v56, 0
	v_mov_b32_e32 v57, 0
	v_mul_u32_u24_e32 v26, s28, v20
	v_add_lshl_u32 v26, v26, v21, 2
	s_lshl_b32 s0, s28, 7
	v_add_u32_e32 v27, s0, v26
	v_cmp_gt_i32_e32 vcc, s29, v21
	s_and_saveexec_b64 s[0:1], vcc
	global_load_dwordx4 v[50:53], v26, s[26:27] nt
	global_load_dwordx4 v[54:57], v27, s[26:27] nt
	s_mov_b64 exec, s[0:1]
	s_add_u32 s24, s24, 0xe0
	s_min_u32 s0, s24, 4479
	s_mov_b32 s21, s0
	s_mov_b32 s0, s21
	s_cmpk_lt_u32 s0, 9600
	s_cbranch_scc0 .Ltc2_c41
	s_and_b32 s1, s0, 31
	s_lshl_b32 s1, s1, 6
	s_lshr_b32 s21, s0, 5
	s_lshl_b32 s21, s21, 6
	s_movk_i32 s29, 64
	s_cmpk_lt_u32 s21, 7680
	s_cbranch_scc1 .Ltc2_n43
	s_cmpk_lt_u32 s21, 18944
	s_cbranch_scc0 .Ltc2_t42
	s_add_u32 s21, s21, 48
	s_branch .Ltc2_n43

; __device__ __forceinline__ void tconv_tile(LAS float* tile, const float* src, int ld, int k0, int n0, int mode, bf16_t* dst, int K) {
;     ...
;     for (int it = 0; it < 2; ++it) { const int idx = tid + it * 512, kk = idx >> 4, n4 = (idx & 15) * 4, nn = n0 + n4; int oc = nn; bool valid = true;
;         if (mode == 1) { if (nn < 7680) oc = nn; else if (nn < 18944) oc = nn + 48; else if (nn < INW) oc = 7680 + (nn - 18944); else valid = false; }
;         f32x4 v = (f32x4){0.f, 0.f, 0.f, 0.f}; if (valid) v = *(const f32x4*)(src + (size_t)(k0 + kk) * ld + oc);
; __device__ __forceinline__ void prologue(LAS unsigned char* lds, const Ctx& P, int l) {
;     ...
;     for (int t = blockIdx.x; t < T_ALL; t += G) {
;         int q = t;
;         if (q < T_IN) { const int kt = q & 31, ntl = q >> 5; tconv_tile(tile, P.in[3] + (size_t)l * DM * INW, INW, kt * 64, ntl * 64, 1, (bf16_t*)(ws + WS_WIN), DM); continue; }
.Ltc2_d40:
	v_mov_b32_e32 v58, 0
	v_mov_b32_e32 v59, 0
	v_mov_b32_e32 v60, 0
	v_mov_b32_e32 v61, 0
	v_mov_b32_e32 v62, 0
	v_mov_b32_e32 v63, 0
	v_mov_b32_e32 v64, 0
	v_mov_b32_e32 v65, 0
	v_mul_u32_u24_e32 v26, s28, v20
	v_add_lshl_u32 v26, v26, v21, 2
	s_lshl_b32 s0, s28, 7
	v_add_u32_e32 v27, s0, v26
	v_cmp_gt_i32_e32 vcc, s29, v21
	s_and_saveexec_b64 s[0:1], vcc
	global_load_dwordx4 v[58:61], v26, s[26:27] nt
	global_load_dwordx4 v[62:65], v27, s[26:27] nt
	s_mov_b64 exec, s[0:1]
	s_add_u32 s24, s24, 0xe0
	s_min_u32 s0, s24, 4479
	s_mov_b32 s21, s0
	s_mov_b32 s0, s21
	s_cmpk_lt_u32 s0, 9600
	s_cbranch_scc0 .Ltc2_c54
	s_and_b32 s1, s0, 31
	s_lshl_b32 s1, s1, 6
	s_lshr_b32 s21, s0, 5
	s_lshl_b32 s21, s21, 6
	s_movk_i32 s29, 64
	s_cmpk_lt_u32 s21, 7680
	s_cbranch_scc1 .Ltc2_n56
	s_cmpk_lt_u32 s21, 18944
	s_cbranch_scc0 .Ltc2_t55
	s_add_u32 s21, s21, 48
	s_branch .Ltc2_n56

; __device__ __forceinline__ void tconv_tile(LAS float* tile, const float* src, int ld, int k0, int n0, int mode, bf16_t* dst, int K) {
;     ...
;     for (int it = 0; it < 2; ++it) { const int idx = tid + it * 512, kk = idx >> 4, n4 = (idx & 15) * 4, nn = n0 + n4; int oc = nn; bool valid = true;
;         if (mode == 1) { if (nn < 7680) oc = nn; else if (nn < 18944) oc = nn + 48; else if (nn < INW) oc = 7680 + (nn - 18944); else valid = false; }
;         f32x4 v = (f32x4){0.f, 0.f, 0.f, 0.f}; if (valid) v = *(const f32x4*)(src + (size_t)(k0 + kk) * ld + oc);
; __device__ __forceinline__ void prologue(LAS unsigned char* lds, const Ctx& P, int l) {
;     ...
;     for (int t = blockIdx.x; t < T_ALL; t += G) {
;         int q = t;
;         if (q < T_IN) { const int kt = q & 31, ntl = q >> 5; tconv_tile(tile, P.in[3] + (size_t)l * DM * INW, INW, kt * 64, ntl * 64, 1, (bf16_t*)(ws + WS_WIN), DM); continue; }
.Ltc2_d53:
	v_mov_b32_e32 v78, 0
	v_mov_b32_e32 v79, 0
	v_mov_b32_e32 v80, 0
	v_mov_b32_e32 v81, 0
	v_mov_b32_e32 v82, 0
	v_mov_b32_e32 v83, 0
	v_mov_b32_e32 v84, 0
	v_mov_b32_e32 v85, 0
	v_mul_u32_u24_e32 v26, s28, v20
	v_add_lshl_u32 v26, v26, v21, 2
	s_lshl_b32 s0, s28, 7
	v_add_u32_e32 v27, s0, v26
	v_cmp_gt_i32_e32 vcc, s29, v21
	s_and_saveexec_b64 s[0:1], vcc
	global_load_dwordx4 v[78:81], v26, s[26:27] nt
	global_load_dwordx4 v[82:85], v27, s[26:27] nt
	s_mov_b64 exec, s[0:1]
	s_add_u32 s24, s24, 0xe0
	s_min_u32 s0, s24, 4479
	s_mov_b32 s21, s0
	s_mov_b32 s0, s21
	s_cmpk_lt_u32 s0, 9600
	s_cbranch_scc0 .Ltc2_c67
	s_and_b32 s1, s0, 31
	s_lshl_b32 s1, s1, 6
	s_lshr_b32 s21, s0, 5
	s_lshl_b32 s21, s21, 6
	s_movk_i32 s29, 64
	s_cmpk_lt_u32 s21, 7680
	s_cbranch_scc1 .Ltc2_n69
	s_cmpk_lt_u32 s21, 18944
	s_cbranch_scc0 .Ltc2_t68
	s_add_u32 s21, s21, 48
	s_branch .Ltc2_n69

; __device__ __forceinline__ unsigned cvt_pk_bf16(float lo, float hi) { unsigned r; asm("v_cvt_pk_bf16_f32 %0, %1, %2" : "=v"(r) : "v"(lo), "v"(hi)); return r; }
; __device__ __forceinline__ void tconv_tile(LAS float* tile, const float* src, int ld, int k0, int n0, int mode, bf16_t* dst, int K) {
;     ...
;     for (int it = 0; it < 2; ++it) { const int idx = tid + it * 512, kk = idx >> 4, n4 = (idx & 15) * 4, nn = n0 + n4; int oc = nn; bool valid = true;
;         if (mode == 1) { if (nn < 7680) oc = nn; else if (nn < 18944) oc = nn + 48; else if (nn < INW) oc = 7680 + (nn - 18944); else valid = false; }
;         f32x4 v = (f32x4){0.f, 0.f, 0.f, 0.f}; if (valid) v = *(const f32x4*)(src + (size_t)(k0 + kk) * ld + oc);
;         tile[kk * 65 + n4 + 0] = v[0]; tile[kk * 65 + n4 + 1] = v[1]; tile[kk * 65 + n4 + 2] = v[2]; tile[kk * 65 + n4 + 3] = v[3]; }
;     __syncthreads();
;     { const int n = tid >> 3, k8 = (tid & 7) * 8; float v[8];
; #pragma unroll
;         for (int e = 0; e < 8; ++e) v[e] = tile[(k8 + e) * 65 + n];
;         u32x4 w; w.x = cvt_pk_bf16(v[0], v[1]); w.y = cvt_pk_bf16(v[2], v[3]); w.z = cvt_pk_bf16(v[4], v[5]); w.w = cvt_pk_bf16(v[6], v[7]);
;         *(u32x4*)(dst + (size_t)(n0 + n) * K + k0 + k8) = w; }
; __device__ __forceinline__ void prologue(LAS unsigned char* lds, const Ctx& P, int l) {
;     ...
;     for (int t = blockIdx.x; t < T_ALL; t += G) {
;         int q = t;
;         if (q < T_IN) { const int kt = q & 31, ntl = q >> 5; tconv_tile(tile, P.in[3] + (size_t)l * DM * INW, INW, kt * 64, ntl * 64, 1, (bf16_t*)(ws + WS_WIN), DM); continue; }
.Ltc2_d66:
	v_mov_b32_e32 v86, 0
	v_mov_b32_e32 v87, 0
	v_mov_b32_e32 v88, 0
	v_mov_b32_e32 v89, 0
	v_mov_b32_e32 v90, 0
	v_mov_b32_e32 v91, 0
	v_mov_b32_e32 v92, 0
	v_mov_b32_e32 v93, 0
	v_mul_u32_u24_e32 v26, s28, v20
	v_add_lshl_u32 v26, v26, v21, 2
	s_lshl_b32 s0, s28, 7
	v_add_u32_e32 v27, s0, v26
	v_cmp_gt_i32_e32 vcc, s29, v21
	s_and_saveexec_b64 s[0:1], vcc
	global_load_dwordx4 v[86:89], v26, s[26:27] nt
	global_load_dwordx4 v[90:93], v27, s[26:27] nt
	s_mov_b64 exec, s[0:1]
	s_add_u32 s24, s24, 0xe0
	s_cmpk_ge_u32 s25, 4480
	s_cbranch_scc1 .Ltc2_exit
	s_waitcnt vmcnt(10)
	v_add_u32_e32 v28, 0, v22
	ds_write2_b32 v28, v34, v35 offset1:1
	ds_write2_b32 v28, v36, v37 offset0:2 offset1:3
	v_add_u32_e32 v28, 0x2080, v28
	ds_write2_b32 v28, v38, v39 offset1:1
	ds_write2_b32 v28, v40, v41 offset0:2 offset1:3
	s_mov_b32 s21, s25
	s_mov_b32 s0, s21
	s_cmpk_lt_u32 s0, 9600
	s_cbranch_scc0 .Ltc2_c80
	s_and_b32 s1, s0, 31
	s_lshl_b32 s1, s1, 6
	s_lshr_b32 s21, s0, 5
	s_lshl_b32 s21, s21, 17
	s_add_u32 s1, s1, s21
	s_lshl_b32 s1, s1, 1
	s_add_u32 s1, s1, 0x4001000
	s_add_u32 s30, s68, s1
	s_addc_u32 s31, s69, 0
	s_movk_i32 s20, 0x800
	s_branch .Ltc2_d79

; __device__ __forceinline__ unsigned cvt_pk_bf16(float lo, float hi) { unsigned r; asm("v_cvt_pk_bf16_f32 %0, %1, %2" : "=v"(r) : "v"(lo), "v"(hi)); return r; }
; __device__ __forceinline__ void tconv_tile(LAS float* tile, const float* src, int ld, int k0, int n0, int mode, bf16_t* dst, int K) {
;     ...
;     for (int it = 0; it < 2; ++it) { const int idx = tid + it * 512, kk = idx >> 4, n4 = (idx & 15) * 4, nn = n0 + n4; int oc = nn; bool valid = true;
;         if (mode == 1) { if (nn < 7680) oc = nn; else if (nn < 18944) oc = nn + 48; else if (nn < INW) oc = 7680 + (nn - 18944); else valid = false; }
;         f32x4 v = (f32x4){0.f, 0.f, 0.f, 0.f}; if (valid) v = *(const f32x4*)(src + (size_t)(k0 + kk) * ld + oc);
;         tile[kk * 65 + n4 + 0] = v[0]; tile[kk * 65 + n4 + 1] = v[1]; tile[kk * 65 + n4 + 2] = v[2]; tile[kk * 65 + n4 + 3] = v[3]; }
;     __syncthreads();
;     { const int n = tid >> 3, k8 = (tid & 7) * 8; float v[8];
; #pragma unroll
;         for (int e = 0; e < 8; ++e) v[e] = tile[(k8 + e) * 65 + n];
;         u32x4 w; w.x = cvt_pk_bf16(v[0], v[1]); w.y = cvt_pk_bf16(v[2], v[3]); w.z = cvt_pk_bf16(v[4], v[5]); w.w = cvt_pk_bf16(v[6], v[7]);
;         *(u32x4*)(dst + (size_t)(n0 + n) * K + k0 + k8) = w; }
.Ltc2_d79:
	v_mul_u32_u24_e32 v29, s20, v24
	v_add_lshl_u32 v29, v29, v25, 1
	s_waitcnt lgkmcnt(0)
	s_barrier
	v_add_u32_e32 v28, 0, v23
	ds_read2_b32 v[2:3], v28 offset1:65
	ds_read2_b32 v[4:5], v28 offset0:130 offset1:195
	v_add_u32_e32 v28, 0x400, v28
	ds_read2_b32 v[6:7], v28 offset0:4 offset1:69
	ds_read2_b32 v[10:11], v28 offset0:134 offset1:199
	s_waitcnt lgkmcnt(3)
	v_cvt_pk_bf16_f32 v2, v2, v3
	s_waitcnt lgkmcnt(2)
	v_cvt_pk_bf16_f32 v3, v4, v5
	s_waitcnt lgkmcnt(1)
	v_cvt_pk_bf16_f32 v4, v6, v7
	s_waitcnt lgkmcnt(0)
	v_cvt_pk_bf16_f32 v5, v10, v11
	global_store_dwordx4 v29, v[2:5], s[30:31] nt
	s_add_u32 s25, s25, 0xe0
	s_min_u32 s0, s24, 4479
	s_mov_b32 s21, s0
	s_mov_b32 s0, s21
	s_cmpk_lt_u32 s0, 9600
	s_cbranch_scc0 .Ltc2_c87
	s_and_b32 s1, s0, 31
	s_lshl_b32 s1, s1, 6
	s_lshr_b32 s21, s0, 5
	s_lshl_b32 s21, s21, 6
	s_movk_i32 s29, 64
	s_cmpk_lt_u32 s21, 7680
	s_cbranch_scc1 .Ltc2_n89
	s_cmpk_lt_u32 s21, 18944
	s_cbranch_scc0 .Ltc2_t88
	s_add_u32 s21, s21, 48
	s_branch .Ltc2_n89

; __device__ __forceinline__ unsigned cvt_pk_bf16(float lo, float hi) { unsigned r; asm("v_cvt_pk_bf16_f32 %0, %1, %2" : "=v"(r) : "v"(lo), "v"(hi)); return r; }
; __device__ __forceinline__ void tconv_tile(LAS float* tile, const float* src, int ld, int k0, int n0, int mode, bf16_t* dst, int K) {
;     ...
;     for (int it = 0; it < 2; ++it) { const int idx = tid + it * 512, kk = idx >> 4, n4 = (idx & 15) * 4, nn = n0 + n4; int oc = nn; bool valid = true;
;         if (mode == 1) { if (nn < 7680) oc = nn; else if (nn < 18944) oc = nn + 48; else if (nn < INW) oc = 7680 + (nn - 18944); else valid = false; }
;         f32x4 v = (f32x4){0.f, 0.f, 0.f, 0.f}; if (valid) v = *(const f32x4*)(src + (size_t)(k0 + kk) * ld + oc);
;         tile[kk * 65 + n4 + 0] = v[0]; tile[kk * 65 + n4 + 1] = v[1]; tile[kk * 65 + n4 + 2] = v[2]; tile[kk * 65 + n4 + 3] = v[3]; }
;     __syncthreads();
;     { const int n = tid >> 3, k8 = (tid & 7) * 8; float v[8];
; #pragma unroll
;         for (int e = 0; e < 8; ++e) v[e] = tile[(k8 + e) * 65 + n];
;         u32x4 w; w.x = cvt_pk_bf16(v[0], v[1]); w.y = cvt_pk_bf16(v[2], v[3]); w.z = cvt_pk_bf16(v[4], v[5]); w.w = cvt_pk_bf16(v[6], v[7]);
;         *(u32x4*)(dst + (size_t)(n0 + n) * K + k0 + k8) = w; }
; __device__ __forceinline__ void prologue(LAS unsigned char* lds, const Ctx& P, int l) {
;     ...
;     for (int t = blockIdx.x; t < T_ALL; t += G) {
;         int q = t;
;         if (q < T_IN) { const int kt = q & 31, ntl = q >> 5; tconv_tile(tile, P.in[3] + (size_t)l * DM * INW, INW, kt * 64, ntl * 64, 1, (bf16_t*)(ws + WS_WIN), DM); continue; }
.Ltc2_d86:
	v_mov_b32_e32 v34, 0
	v_mov_b32_e32 v35, 0
	v_mov_b32_e32 v36, 0
	v_mov_b32_e32 v37, 0
	v_mov_b32_e32 v38, 0
	v_mov_b32_e32 v39, 0
	v_mov_b32_e32 v40, 0
	v_mov_b32_e32 v41, 0
	v_mul_u32_u24_e32 v26, s28, v20
	v_add_lshl_u32 v26, v26, v21, 2
	s_lshl_b32 s0, s28, 7
	v_add_u32_e32 v27, s0, v26
	v_cmp_gt_i32_e32 vcc, s29, v21
	s_and_saveexec_b64 s[0:1], vcc
	global_load_dwordx4 v[34:37], v26, s[26:27] nt
	global_load_dwordx4 v[38:41], v27, s[26:27] nt
	s_mov_b64 exec, s[0:1]
	s_add_u32 s24, s24, 0xe0
	s_cmpk_ge_u32 s25, 4480
	s_cbranch_scc1 .Ltc2_exit
	s_waitcnt vmcnt(11)
	v_add_u32_e32 v28, 16896, v22
	ds_write2_b32 v28, v42, v43 offset1:1
	ds_write2_b32 v28, v44, v45 offset0:2 offset1:3
	v_add_u32_e32 v28, 0x2080, v28
	ds_write2_b32 v28, v46, v47 offset1:1
	ds_write2_b32 v28, v48, v49 offset0:2 offset1:3
	s_mov_b32 s21, s25
	s_mov_b32 s0, s21
	s_cmpk_lt_u32 s0, 9600
	s_cbranch_scc0 .Ltc2_c100
	s_and_b32 s1, s0, 31
	s_lshl_b32 s1, s1, 6
	s_lshr_b32 s21, s0, 5
	s_lshl_b32 s21, s21, 17
	s_add_u32 s1, s1, s21
	s_lshl_b32 s1, s1, 1
	s_add_u32 s1, s1, 0x4001000
	s_add_u32 s30, s68, s1
	s_addc_u32 s31, s69, 0
	s_movk_i32 s20, 0x800
	s_branch .Ltc2_d99

; __device__ __forceinline__ unsigned cvt_pk_bf16(float lo, float hi) { unsigned r; asm("v_cvt_pk_bf16_f32 %0, %1, %2" : "=v"(r) : "v"(lo), "v"(hi)); return r; }
; __device__ __forceinline__ void tconv_tile(LAS float* tile, const float* src, int ld, int k0, int n0, int mode, bf16_t* dst, int K) {
;     ...
;     for (int it = 0; it < 2; ++it) { const int idx = tid + it * 512, kk = idx >> 4, n4 = (idx & 15) * 4, nn = n0 + n4; int oc = nn; bool valid = true;
;         if (mode == 1) { if (nn < 7680) oc = nn; else if (nn < 18944) oc = nn + 48; else if (nn < INW) oc = 7680 + (nn - 18944); else valid = false; }
;         f32x4 v = (f32x4){0.f, 0.f, 0.f, 0.f}; if (valid) v = *(const f32x4*)(src + (size_t)(k0 + kk) * ld + oc);
;         tile[kk * 65 + n4 + 0] = v[0]; tile[kk * 65 + n4 + 1] = v[1]; tile[kk * 65 + n4 + 2] = v[2]; tile[kk * 65 + n4 + 3] = v[3]; }
;     __syncthreads();
;     { const int n = tid >> 3, k8 = (tid & 7) * 8; float v[8];
; #pragma unroll
;         for (int e = 0; e < 8; ++e) v[e] = tile[(k8 + e) * 65 + n];
;         u32x4 w; w.x = cvt_pk_bf16(v[0], v[1]); w.y = cvt_pk_bf16(v[2], v[3]); w.z = cvt_pk_bf16(v[4], v[5]); w.w = cvt_pk_bf16(v[6], v[7]);
;         *(u32x4*)(dst + (size_t)(n0 + n) * K + k0 + k8) = w; }
.Ltc2_d99:
	v_mul_u32_u24_e32 v29, s20, v24
	v_add_lshl_u32 v29, v29, v25, 1
	s_waitcnt lgkmcnt(0)
	s_barrier
	v_add_u32_e32 v28, 16896, v23
	ds_read2_b32 v[2:3], v28 offset1:65
	ds_read2_b32 v[4:5], v28 offset0:130 offset1:195
	v_add_u32_e32 v28, 0x400, v28
	ds_read2_b32 v[6:7], v28 offset0:4 offset1:69
	ds_read2_b32 v[10:11], v28 offset0:134 offset1:199
	s_waitcnt lgkmcnt(3)
	v_cvt_pk_bf16_f32 v2, v2, v3
	s_waitcnt lgkmcnt(2)
	v_cvt_pk_bf16_f32 v3, v4, v5
	s_waitcnt lgkmcnt(1)
	v_cvt_pk_bf16_f32 v4, v6, v7
	s_waitcnt lgkmcnt(0)
	v_cvt_pk_bf16_f32 v5, v10, v11
	global_store_dwordx4 v29, v[2:5], s[30:31] nt
	s_add_u32 s25, s25, 0xe0
	s_min_u32 s0, s24, 4479
	s_mov_b32 s21, s0
	s_mov_b32 s0, s21
	s_cmpk_lt_u32 s0, 9600
	s_cbranch_scc0 .Ltc2_c107
	s_and_b32 s1, s0, 31
	s_lshl_b32 s1, s1, 6
	s_lshr_b32 s21, s0, 5
	s_lshl_b32 s21, s21, 6
	s_movk_i32 s29, 64
	s_cmpk_lt_u32 s21, 7680
	s_cbranch_scc1 .Ltc2_n109
	s_cmpk_lt_u32 s21, 18944
	s_cbranch_scc0 .Ltc2_t108
	s_add_u32 s21, s21, 48
	s_branch .Ltc2_n109

; __device__ __forceinline__ unsigned cvt_pk_bf16(float lo, float hi) { unsigned r; asm("v_cvt_pk_bf16_f32 %0, %1, %2" : "=v"(r) : "v"(lo), "v"(hi)); return r; }
; __device__ __forceinline__ void tconv_tile(LAS float* tile, const float* src, int ld, int k0, int n0, int mode, bf16_t* dst, int K) {
;     ...
;     for (int it = 0; it < 2; ++it) { const int idx = tid + it * 512, kk = idx >> 4, n4 = (idx & 15) * 4, nn = n0 + n4; int oc = nn; bool valid = true;
;         if (mode == 1) { if (nn < 7680) oc = nn; else if (nn < 18944) oc = nn + 48; else if (nn < INW) oc = 7680 + (nn - 18944); else valid = false; }
;         f32x4 v = (f32x4){0.f, 0.f, 0.f, 0.f}; if (valid) v = *(const f32x4*)(src + (size_t)(k0 + kk) * ld + oc);
;         tile[kk * 65 + n4 + 0] = v[0]; tile[kk * 65 + n4 + 1] = v[1]; tile[kk * 65 + n4 + 2] = v[2]; tile[kk * 65 + n4 + 3] = v[3]; }
;     __syncthreads();
;     { const int n = tid >> 3, k8 = (tid & 7) * 8; float v[8];
; #pragma unroll
;         for (int e = 0; e < 8; ++e) v[e] = tile[(k8 + e) * 65 + n];
;         u32x4 w; w.x = cvt_pk_bf16(v[0], v[1]); w.y = cvt_pk_bf16(v[2], v[3]); w.z = cvt_pk_bf16(v[4], v[5]); w.w = cvt_pk_bf16(v[6], v[7]);
;         *(u32x4*)(dst + (size_t)(n0 + n) * K + k0 + k8) = w; }
; __device__ __forceinline__ void prologue(LAS unsigned char* lds, const Ctx& P, int l) {
;     ...
;     for (int t = blockIdx.x; t < T_ALL; t += G) {
;         int q = t;
;         if (q < T_IN) { const int kt = q & 31, ntl = q >> 5; tconv_tile(tile, P.in[3] + (size_t)l * DM * INW, INW, kt * 64, ntl * 64, 1, (bf16_t*)(ws + WS_WIN), DM); continue; }
.Ltc2_d106:
	v_mov_b32_e32 v42, 0
	v_mov_b32_e32 v43, 0
	v_mov_b32_e32 v44, 0
	v_mov_b32_e32 v45, 0
	v_mov_b32_e32 v46, 0
	v_mov_b32_e32 v47, 0
	v_mov_b32_e32 v48, 0
	v_mov_b32_e32 v49, 0
	v_mul_u32_u24_e32 v26, s28, v20
	v_add_lshl_u32 v26, v26, v21, 2
	s_lshl_b32 s0, s28, 7
	v_add_u32_e32 v27, s0, v26
	v_cmp_gt_i32_e32 vcc, s29, v21
	s_and_saveexec_b64 s[0:1], vcc
	global_load_dwordx4 v[42:45], v26, s[26:27] nt
	global_load_dwordx4 v[46:49], v27, s[26:27] nt
	s_mov_b64 exec, s[0:1]
	s_add_u32 s24, s24, 0xe0
	s_cmpk_ge_u32 s25, 4480
	s_cbranch_scc1 .Ltc2_exit
	s_waitcnt vmcnt(12)
	v_add_u32_e32 v28, 0, v22
	ds_write2_b32 v28, v50, v51 offset1:1
	ds_write2_b32 v28, v52, v53 offset0:2 offset1:3
	v_add_u32_e32 v28, 0x2080, v28
	ds_write2_b32 v28, v54, v55 offset1:1
	ds_write2_b32 v28, v56, v57 offset0:2 offset1:3
	s_mov_b32 s21, s25
	s_mov_b32 s0, s21
	s_cmpk_lt_u32 s0, 9600
	s_cbranch_scc0 .Ltc2_c120
	s_and_b32 s1, s0, 31
	s_lshl_b32 s1, s1, 6
	s_lshr_b32 s21, s0, 5
	s_lshl_b32 s21, s21, 17
	s_add_u32 s1, s1, s21
	s_lshl_b32 s1, s1, 1
	s_add_u32 s1, s1, 0x4001000
	s_add_u32 s30, s68, s1
	s_addc_u32 s31, s69, 0
	s_movk_i32 s20, 0x800
	s_branch .Ltc2_d119

; __device__ __forceinline__ unsigned cvt_pk_bf16(float lo, float hi) { unsigned r; asm("v_cvt_pk_bf16_f32 %0, %1, %2" : "=v"(r) : "v"(lo), "v"(hi)); return r; }
; __device__ __forceinline__ void tconv_tile(LAS float* tile, const float* src, int ld, int k0, int n0, int mode, bf16_t* dst, int K) {
;     ...
;     for (int it = 0; it < 2; ++it) { const int idx = tid + it * 512, kk = idx >> 4, n4 = (idx & 15) * 4, nn = n0 + n4; int oc = nn; bool valid = true;
;         if (mode == 1) { if (nn < 7680) oc = nn; else if (nn < 18944) oc = nn + 48; else if (nn < INW) oc = 7680 + (nn - 18944); else valid = false; }
;         f32x4 v = (f32x4){0.f, 0.f, 0.f, 0.f}; if (valid) v = *(const f32x4*)(src + (size_t)(k0 + kk) * ld + oc);
;         tile[kk * 65 + n4 + 0] = v[0]; tile[kk * 65 + n4 + 1] = v[1]; tile[kk * 65 + n4 + 2] = v[2]; tile[kk * 65 + n4 + 3] = v[3]; }
;     __syncthreads();
;     { const int n = tid >> 3, k8 = (tid & 7) * 8; float v[8];
; #pragma unroll
;         for (int e = 0; e < 8; ++e) v[e] = tile[(k8 + e) * 65 + n];
;         u32x4 w; w.x = cvt_pk_bf16(v[0], v[1]); w.y = cvt_pk_bf16(v[2], v[3]); w.z = cvt_pk_bf16(v[4], v[5]); w.w = cvt_pk_bf16(v[6], v[7]);
;         *(u32x4*)(dst + (size_t)(n0 + n) * K + k0 + k8) = w; }
; __device__ __forceinline__ void prologue(LAS unsigned char* lds, const Ctx& P, int l) {
;     ...
;     for (int t = blockIdx.x; t < T_ALL; t += G) {
;         int q = t;
;         if (q < T_IN) { const int kt = q & 31, ntl = q >> 5; tconv_tile(tile, P.in[3] + (size_t)l * DM * INW, INW, kt * 64, ntl * 64, 1, (bf16_t*)(ws + WS_WIN), DM); continue; }
.Ltc2_d126:
	v_mov_b32_e32 v50, 0
	v_mov_b32_e32 v51, 0
	v_mov_b32_e32 v52, 0
	v_mov_b32_e32 v53, 0
	v_mov_b32_e32 v54, 0
	v_mov_b32_e32 v55, 0
	v_mov_b32_e32 v56, 0
	v_mov_b32_e32 v57, 0
	v_mul_u32_u24_e32 v26, s28, v20
	v_add_lshl_u32 v26, v26, v21, 2
	s_lshl_b32 s0, s28, 7
	v_add_u32_e32 v27, s0, v26
	v_cmp_gt_i32_e32 vcc, s29, v21
	s_and_saveexec_b64 s[0:1], vcc
	global_load_dwordx4 v[50:53], v26, s[26:27] nt
	global_load_dwordx4 v[54:57], v27, s[26:27] nt
	s_mov_b64 exec, s[0:1]
	s_add_u32 s24, s24, 0xe0
	s_cmpk_ge_u32 s25, 4480
	s_cbranch_scc1 .Ltc2_exit
	s_waitcnt vmcnt(13)
	v_add_u32_e32 v28, 16896, v22
	ds_write2_b32 v28, v58, v59 offset1:1
	ds_write2_b32 v28, v60, v61 offset0:2 offset1:3
	v_add_u32_e32 v28, 0x2080, v28
	ds_write2_b32 v28, v62, v63 offset1:1
	ds_write2_b32 v28, v64, v65 offset0:2 offset1:3
	s_mov_b32 s21, s25
	s_mov_b32 s0, s21
	s_cmpk_lt_u32 s0, 9600
	s_cbranch_scc0 .Ltc2_c140
	s_and_b32 s1, s0, 31
	s_lshl_b32 s1, s1, 6
	s_lshr_b32 s21, s0, 5
	s_lshl_b32 s21, s21, 17
	s_add_u32 s1, s1, s21
	s_lshl_b32 s1, s1, 1
	s_add_u32 s1, s1, 0x4001000
	s_add_u32 s30, s68, s1
	s_addc_u32 s31, s69, 0
	s_movk_i32 s20, 0x800
	s_branch .Ltc2_d139

; __device__ __forceinline__ unsigned cvt_pk_bf16(float lo, float hi) { unsigned r; asm("v_cvt_pk_bf16_f32 %0, %1, %2" : "=v"(r) : "v"(lo), "v"(hi)); return r; }
; __device__ __forceinline__ void tconv_tile(LAS float* tile, const float* src, int ld, int k0, int n0, int mode, bf16_t* dst, int K) {
;     ...
;     for (int it = 0; it < 2; ++it) { const int idx = tid + it * 512, kk = idx >> 4, n4 = (idx & 15) * 4, nn = n0 + n4; int oc = nn; bool valid = true;
;         if (mode == 1) { if (nn < 7680) oc = nn; else if (nn < 18944) oc = nn + 48; else if (nn < INW) oc = 7680 + (nn - 18944); else valid = false; }
;         f32x4 v = (f32x4){0.f, 0.f, 0.f, 0.f}; if (valid) v = *(const f32x4*)(src + (size_t)(k0 + kk) * ld + oc);
;         tile[kk * 65 + n4 + 0] = v[0]; tile[kk * 65 + n4 + 1] = v[1]; tile[kk * 65 + n4 + 2] = v[2]; tile[kk * 65 + n4 + 3] = v[3]; }
;     __syncthreads();
;     { const int n = tid >> 3, k8 = (tid & 7) * 8; float v[8];
; #pragma unroll
;         for (int e = 0; e < 8; ++e) v[e] = tile[(k8 + e) * 65 + n];
;         u32x4 w; w.x = cvt_pk_bf16(v[0], v[1]); w.y = cvt_pk_bf16(v[2], v[3]); w.z = cvt_pk_bf16(v[4], v[5]); w.w = cvt_pk_bf16(v[6], v[7]);
;         *(u32x4*)(dst + (size_t)(n0 + n) * K + k0 + k8) = w; }
; __device__ __forceinline__ void prologue(LAS unsigned char* lds, const Ctx& P, int l) {
;     ...
;     for (int t = blockIdx.x; t < T_ALL; t += G) {
;         int q = t;
;         if (q < T_IN) { const int kt = q & 31, ntl = q >> 5; tconv_tile(tile, P.in[3] + (size_t)l * DM * INW, INW, kt * 64, ntl * 64, 1, (bf16_t*)(ws + WS_WIN), DM); continue; }
.Ltc2_d146:
	v_mov_b32_e32 v58, 0
	v_mov_b32_e32 v59, 0
	v_mov_b32_e32 v60, 0
	v_mov_b32_e32 v61, 0
	v_mov_b32_e32 v62, 0
	v_mov_b32_e32 v63, 0
	v_mov_b32_e32 v64, 0
	v_mov_b32_e32 v65, 0
	v_mul_u32_u24_e32 v26, s28, v20
	v_add_lshl_u32 v26, v26, v21, 2
	s_lshl_b32 s0, s28, 7
	v_add_u32_e32 v27, s0, v26
	v_cmp_gt_i32_e32 vcc, s29, v21
	s_and_saveexec_b64 s[0:1], vcc
	global_load_dwordx4 v[58:61], v26, s[26:27] nt
	global_load_dwordx4 v[62:65], v27, s[26:27] nt
	s_mov_b64 exec, s[0:1]
	s_add_u32 s24, s24, 0xe0
	s_cmpk_ge_u32 s25, 4480
	s_cbranch_scc1 .Ltc2_exit
	s_waitcnt vmcnt(14)
	v_add_u32_e32 v28, 0, v22
	ds_write2_b32 v28, v78, v79 offset1:1
	ds_write2_b32 v28, v80, v81 offset0:2 offset1:3
	v_add_u32_e32 v28, 0x2080, v28
	ds_write2_b32 v28, v82, v83 offset1:1
	ds_write2_b32 v28, v84, v85 offset0:2 offset1:3
	s_mov_b32 s21, s25
	s_mov_b32 s0, s21
	s_cmpk_lt_u32 s0, 9600
	s_cbranch_scc0 .Ltc2_c160
	s_and_b32 s1, s0, 31
	s_lshl_b32 s1, s1, 6
	s_lshr_b32 s21, s0, 5
	s_lshl_b32 s21, s21, 17
	s_add_u32 s1, s1, s21
	s_lshl_b32 s1, s1, 1
	s_add_u32 s1, s1, 0x4001000
	s_add_u32 s30, s68, s1
	s_addc_u32 s31, s69, 0
	s_movk_i32 s20, 0x800
	s_branch .Ltc2_d159

; __device__ __forceinline__ unsigned cvt_pk_bf16(float lo, float hi) { unsigned r; asm("v_cvt_pk_bf16_f32 %0, %1, %2" : "=v"(r) : "v"(lo), "v"(hi)); return r; }
; __device__ __forceinline__ void tconv_tile(LAS float* tile, const float* src, int ld, int k0, int n0, int mode, bf16_t* dst, int K) {
;     ...
;     for (int it = 0; it < 2; ++it) { const int idx = tid + it * 512, kk = idx >> 4, n4 = (idx & 15) * 4, nn = n0 + n4; int oc = nn; bool valid = true;
;         if (mode == 1) { if (nn < 7680) oc = nn; else if (nn < 18944) oc = nn + 48; else if (nn < INW) oc = 7680 + (nn - 18944); else valid = false; }
;         f32x4 v = (f32x4){0.f, 0.f, 0.f, 0.f}; if (valid) v = *(const f32x4*)(src + (size_t)(k0 + kk) * ld + oc);
;         tile[kk * 65 + n4 + 0] = v[0]; tile[kk * 65 + n4 + 1] = v[1]; tile[kk * 65 + n4 + 2] = v[2]; tile[kk * 65 + n4 + 3] = v[3]; }
;     __syncthreads();
;     { const int n = tid >> 3, k8 = (tid & 7) * 8; float v[8];
; #pragma unroll
;         for (int e = 0; e < 8; ++e) v[e] = tile[(k8 + e) * 65 + n];
;         u32x4 w; w.x = cvt_pk_bf16(v[0], v[1]); w.y = cvt_pk_bf16(v[2], v[3]); w.z = cvt_pk_bf16(v[4], v[5]); w.w = cvt_pk_bf16(v[6], v[7]);
;         *(u32x4*)(dst + (size_t)(n0 + n) * K + k0 + k8) = w; }
; __device__ __forceinline__ void prologue(LAS unsigned char* lds, const Ctx& P, int l) {
;     ...
;     for (int t = blockIdx.x; t < T_ALL; t += G) {
;         int q = t;
;         if (q < T_IN) { const int kt = q & 31, ntl = q >> 5; tconv_tile(tile, P.in[3] + (size_t)l * DM * INW, INW, kt * 64, ntl * 64, 1, (bf16_t*)(ws + WS_WIN), DM); continue; }
.Ltc2_d166:
	v_mov_b32_e32 v78, 0
	v_mov_b32_e32 v79, 0
	v_mov_b32_e32 v80, 0
	v_mov_b32_e32 v81, 0
	v_mov_b32_e32 v82, 0
	v_mov_b32_e32 v83, 0
	v_mov_b32_e32 v84, 0
	v_mov_b32_e32 v85, 0
	v_mul_u32_u24_e32 v26, s28, v20
	v_add_lshl_u32 v26, v26, v21, 2
	s_lshl_b32 s0, s28, 7
	v_add_u32_e32 v27, s0, v26
	v_cmp_gt_i32_e32 vcc, s29, v21
	s_and_saveexec_b64 s[0:1], vcc
	global_load_dwordx4 v[78:81], v26, s[26:27] nt
	global_load_dwordx4 v[82:85], v27, s[26:27] nt
	s_mov_b64 exec, s[0:1]
	s_add_u32 s24, s24, 0xe0
	s_cmpk_ge_u32 s25, 4480
	s_cbranch_scc1 .Ltc2_exit
	s_waitcnt vmcnt(15)
	v_add_u32_e32 v28, 16896, v22
	ds_write2_b32 v28, v86, v87 offset1:1
	ds_write2_b32 v28, v88, v89 offset0:2 offset1:3
	v_add_u32_e32 v28, 0x2080, v28
	ds_write2_b32 v28, v90, v91 offset1:1
	ds_write2_b32 v28, v92, v93 offset0:2 offset1:3
	s_mov_b32 s21, s25
	s_mov_b32 s0, s21
	s_cmpk_lt_u32 s0, 9600
	s_cbranch_scc0 .Ltc2_c180
	s_and_b32 s1, s0, 31
	s_lshl_b32 s1, s1, 6
	s_lshr_b32 s21, s0, 5
	s_lshl_b32 s21, s21, 17
	s_add_u32 s1, s1, s21
	s_lshl_b32 s1, s1, 1
	s_add_u32 s1, s1, 0x4001000
	s_add_u32 s30, s68, s1
	s_addc_u32 s31, s69, 0
	s_movk_i32 s20, 0x800
	s_branch .Ltc2_d179

; __device__ __forceinline__ void tconv_tile(LAS float* tile, const float* src, int ld, int k0, int n0, int mode, bf16_t* dst, int K) {
;     ...
;     for (int it = 0; it < 2; ++it) { const int idx = tid + it * 512, kk = idx >> 4, n4 = (idx & 15) * 4, nn = n0 + n4; int oc = nn; bool valid = true;
;         if (mode == 1) { if (nn < 7680) oc = nn; else if (nn < 18944) oc = nn + 48; else if (nn < INW) oc = 7680 + (nn - 18944); else valid = false; }
;         f32x4 v = (f32x4){0.f, 0.f, 0.f, 0.f}; if (valid) v = *(const f32x4*)(src + (size_t)(k0 + kk) * ld + oc);
.Ltc2_d186:
	v_mov_b32_e32 v86, 0
	v_mov_b32_e32 v87, 0
	v_mov_b32_e32 v88, 0
	v_mov_b32_e32 v89, 0
	v_mov_b32_e32 v90, 0
	v_mov_b32_e32 v91, 0
	v_mov_b32_e32 v92, 0
	v_mov_b32_e32 v93, 0
	v_mul_u32_u24_e32 v26, s28, v20
	v_add_lshl_u32 v26, v26, v21, 2
	s_lshl_b32 s0, s28, 7
	v_add_u32_e32 v27, s0, v26
	v_cmp_gt_i32_e32 vcc, s29, v21
	s_and_saveexec_b64 s[0:1], vcc
	global_load_dwordx4 v[86:89], v26, s[26:27] nt
	global_load_dwordx4 v[90:93], v27, s[26:27] nt
	s_mov_b64 exec, s[0:1]
	s_add_u32 s24, s24, 0xe0

; __device__ __forceinline__ unsigned cvt_pk_bf16(float lo, float hi) { unsigned r; asm("v_cvt_pk_bf16_f32 %0, %1, %2" : "=v"(r) : "v"(lo), "v"(hi)); return r; }
; __device__ __forceinline__ void tconv_tile(LAS float* tile, const float* src, int ld, int k0, int n0, int mode, bf16_t* dst, int K) {
;     ...
;     for (int it = 0; it < 2; ++it) { const int idx = tid + it * 512, kk = idx >> 4, n4 = (idx & 15) * 4, nn = n0 + n4; int oc = nn; bool valid = true;
;         if (mode == 1) { if (nn < 7680) oc = nn; else if (nn < 18944) oc = nn + 48; else if (nn < INW) oc = 7680 + (nn - 18944); else valid = false; }
;         f32x4 v = (f32x4){0.f, 0.f, 0.f, 0.f}; if (valid) v = *(const f32x4*)(src + (size_t)(k0 + kk) * ld + oc);
;         tile[kk * 65 + n4 + 0] = v[0]; tile[kk * 65 + n4 + 1] = v[1]; tile[kk * 65 + n4 + 2] = v[2]; tile[kk * 65 + n4 + 3] = v[3]; }
;     __syncthreads();
;     { const int n = tid >> 3, k8 = (tid & 7) * 8; float v[8];
; #pragma unroll
;         for (int e = 0; e < 8; ++e) v[e] = tile[(k8 + e) * 65 + n];
;         u32x4 w; w.x = cvt_pk_bf16(v[0], v[1]); w.y = cvt_pk_bf16(v[2], v[3]); w.z = cvt_pk_bf16(v[4], v[5]); w.w = cvt_pk_bf16(v[6], v[7]);
;         *(u32x4*)(dst + (size_t)(n0 + n) * K + k0 + k8) = w; }
; __device__ __forceinline__ void prologue(LAS unsigned char* lds, const Ctx& P, int l) {
;     ...
;     for (int t = blockIdx.x; t < T_ALL; t += G) {
;         int q = t;
;         if (q < T_IN) { const int kt = q & 31, ntl = q >> 5; tconv_tile(tile, P.in[3] + (size_t)l * DM * INW, INW, kt * 64, ntl * 64, 1, (bf16_t*)(ws + WS_WIN), DM); continue; }
.Ltc2_d206:
	v_mov_b32_e32 v34, 0
	v_mov_b32_e32 v35, 0
	v_mov_b32_e32 v36, 0
	v_mov_b32_e32 v37, 0
	v_mov_b32_e32 v38, 0
	v_mov_b32_e32 v39, 0
	v_mov_b32_e32 v40, 0
	v_mov_b32_e32 v41, 0
	v_mul_u32_u24_e32 v26, s28, v20
	v_add_lshl_u32 v26, v26, v21, 2
	s_lshl_b32 s0, s28, 7
	v_add_u32_e32 v27, s0, v26
	v_cmp_gt_i32_e32 vcc, s29, v21
	s_and_saveexec_b64 s[0:1], vcc
	global_load_dwordx4 v[34:37], v26, s[26:27] nt
	global_load_dwordx4 v[38:41], v27, s[26:27] nt
	s_mov_b64 exec, s[0:1]
	s_add_u32 s24, s24, 0xe0
	s_cmpk_ge_u32 s25, 4480
	s_cbranch_scc1 .Ltc2_exit
	s_waitcnt vmcnt(15)
	v_add_u32_e32 v28, 16896, v22
	ds_write2_b32 v28, v42, v43 offset1:1
	ds_write2_b32 v28, v44, v45 offset0:2 offset1:3
	v_add_u32_e32 v28, 0x2080, v28
	ds_write2_b32 v28, v46, v47 offset1:1
	ds_write2_b32 v28, v48, v49 offset0:2 offset1:3
	s_mov_b32 s21, s25
	s_mov_b32 s0, s21
	s_cmpk_lt_u32 s0, 9600
	s_cbranch_scc0 .Ltc2_c220
	s_and_b32 s1, s0, 31
	s_lshl_b32 s1, s1, 6
	s_lshr_b32 s21, s0, 5
	s_lshl_b32 s21, s21, 17
	s_add_u32 s1, s1, s21
	s_lshl_b32 s1, s1, 1
	s_add_u32 s1, s1, 0x4001000
	s_add_u32 s30, s68, s1
	s_addc_u32 s31, s69, 0
	s_movk_i32 s20, 0x800
	s_branch .Ltc2_d219

; __device__ __forceinline__ unsigned cvt_pk_bf16(float lo, float hi) { unsigned r; asm("v_cvt_pk_bf16_f32 %0, %1, %2" : "=v"(r) : "v"(lo), "v"(hi)); return r; }
; __device__ __forceinline__ void tconv_tile(LAS float* tile, const float* src, int ld, int k0, int n0, int mode, bf16_t* dst, int K) {
;     ...
;     for (int it = 0; it < 2; ++it) { const int idx = tid + it * 512, kk = idx >> 4, n4 = (idx & 15) * 4, nn = n0 + n4; int oc = nn; bool valid = true;
;         if (mode == 1) { if (nn < 7680) oc = nn; else if (nn < 18944) oc = nn + 48; else if (nn < INW) oc = 7680 + (nn - 18944); else valid = false; }
;         f32x4 v = (f32x4){0.f, 0.f, 0.f, 0.f}; if (valid) v = *(const f32x4*)(src + (size_t)(k0 + kk) * ld + oc);
;         tile[kk * 65 + n4 + 0] = v[0]; tile[kk * 65 + n4 + 1] = v[1]; tile[kk * 65 + n4 + 2] = v[2]; tile[kk * 65 + n4 + 3] = v[3]; }
;     __syncthreads();
;     { const int n = tid >> 3, k8 = (tid & 7) * 8; float v[8];
; #pragma unroll
;         for (int e = 0; e < 8; ++e) v[e] = tile[(k8 + e) * 65 + n];
;         u32x4 w; w.x = cvt_pk_bf16(v[0], v[1]); w.y = cvt_pk_bf16(v[2], v[3]); w.z = cvt_pk_bf16(v[4], v[5]); w.w = cvt_pk_bf16(v[6], v[7]);
;         *(u32x4*)(dst + (size_t)(n0 + n) * K + k0 + k8) = w; }
; __device__ __forceinline__ void prologue(LAS unsigned char* lds, const Ctx& P, int l) {
;     ...
;     for (int t = blockIdx.x; t < T_ALL; t += G) {
;         int q = t;
;         if (q < T_IN) { const int kt = q & 31, ntl = q >> 5; tconv_tile(tile, P.in[3] + (size_t)l * DM * INW, INW, kt * 64, ntl * 64, 1, (bf16_t*)(ws + WS_WIN), DM); continue; }
.Ltc2_d226:
	v_mov_b32_e32 v42, 0
	v_mov_b32_e32 v43, 0
	v_mov_b32_e32 v44, 0
	v_mov_b32_e32 v45, 0
	v_mov_b32_e32 v46, 0
	v_mov_b32_e32 v47, 0
	v_mov_b32_e32 v48, 0
	v_mov_b32_e32 v49, 0
	v_mul_u32_u24_e32 v26, s28, v20
	v_add_lshl_u32 v26, v26, v21, 2
	s_lshl_b32 s0, s28, 7
	v_add_u32_e32 v27, s0, v26
	v_cmp_gt_i32_e32 vcc, s29, v21
	s_and_saveexec_b64 s[0:1], vcc
	global_load_dwordx4 v[42:45], v26, s[26:27] nt
	global_load_dwordx4 v[46:49], v27, s[26:27] nt
	s_mov_b64 exec, s[0:1]
	s_add_u32 s24, s24, 0xe0
	s_cmpk_ge_u32 s25, 4480
	s_cbranch_scc1 .Ltc2_exit
	s_waitcnt vmcnt(15)
	v_add_u32_e32 v28, 0, v22
	ds_write2_b32 v28, v50, v51 offset1:1
	ds_write2_b32 v28, v52, v53 offset0:2 offset1:3
	v_add_u32_e32 v28, 0x2080, v28
	ds_write2_b32 v28, v54, v55 offset1:1
	ds_write2_b32 v28, v56, v57 offset0:2 offset1:3
	s_mov_b32 s21, s25
	s_mov_b32 s0, s21
	s_cmpk_lt_u32 s0, 9600
	s_cbranch_scc0 .Ltc2_c240
	s_and_b32 s1, s0, 31
	s_lshl_b32 s1, s1, 6
	s_lshr_b32 s21, s0, 5
	s_lshl_b32 s21, s21, 17
	s_add_u32 s1, s1, s21
	s_lshl_b32 s1, s1, 1
	s_add_u32 s1, s1, 0x4001000
	s_add_u32 s30, s68, s1
	s_addc_u32 s31, s69, 0
	s_movk_i32 s20, 0x800
	s_branch .Ltc2_d239

; __device__ __forceinline__ unsigned cvt_pk_bf16(float lo, float hi) { unsigned r; asm("v_cvt_pk_bf16_f32 %0, %1, %2" : "=v"(r) : "v"(lo), "v"(hi)); return r; }
; __device__ __forceinline__ void tconv_tile(LAS float* tile, const float* src, int ld, int k0, int n0, int mode, bf16_t* dst, int K) {
;     ...
;     for (int it = 0; it < 2; ++it) { const int idx = tid + it * 512, kk = idx >> 4, n4 = (idx & 15) * 4, nn = n0 + n4; int oc = nn; bool valid = true;
;         if (mode == 1) { if (nn < 7680) oc = nn; else if (nn < 18944) oc = nn + 48; else if (nn < INW) oc = 7680 + (nn - 18944); else valid = false; }
;         f32x4 v = (f32x4){0.f, 0.f, 0.f, 0.f}; if (valid) v = *(const f32x4*)(src + (size_t)(k0 + kk) * ld + oc);
;         tile[kk * 65 + n4 + 0] = v[0]; tile[kk * 65 + n4 + 1] = v[1]; tile[kk * 65 + n4 + 2] = v[2]; tile[kk * 65 + n4 + 3] = v[3]; }
;     __syncthreads();
;     { const int n = tid >> 3, k8 = (tid & 7) * 8; float v[8];
; #pragma unroll
;         for (int e = 0; e < 8; ++e) v[e] = tile[(k8 + e) * 65 + n];
;         u32x4 w; w.x = cvt_pk_bf16(v[0], v[1]); w.y = cvt_pk_bf16(v[2], v[3]); w.z = cvt_pk_bf16(v[4], v[5]); w.w = cvt_pk_bf16(v[6], v[7]);
;         *(u32x4*)(dst + (size_t)(n0 + n) * K + k0 + k8) = w; }
; __device__ __forceinline__ void prologue(LAS unsigned char* lds, const Ctx& P, int l) {
;     ...
;     for (int t = blockIdx.x; t < T_ALL; t += G) {
;         int q = t;
;         if (q < T_IN) { const int kt = q & 31, ntl = q >> 5; tconv_tile(tile, P.in[3] + (size_t)l * DM * INW, INW, kt * 64, ntl * 64, 1, (bf16_t*)(ws + WS_WIN), DM); continue; }
.Ltc2_d246:
	v_mov_b32_e32 v50, 0
	v_mov_b32_e32 v51, 0
	v_mov_b32_e32 v52, 0
	v_mov_b32_e32 v53, 0
	v_mov_b32_e32 v54, 0
	v_mov_b32_e32 v55, 0
	v_mov_b32_e32 v56, 0
	v_mov_b32_e32 v57, 0
	v_mul_u32_u24_e32 v26, s28, v20
	v_add_lshl_u32 v26, v26, v21, 2
	s_lshl_b32 s0, s28, 7
	v_add_u32_e32 v27, s0, v26
	v_cmp_gt_i32_e32 vcc, s29, v21
	s_and_saveexec_b64 s[0:1], vcc
	global_load_dwordx4 v[50:53], v26, s[26:27] nt
	global_load_dwordx4 v[54:57], v27, s[26:27] nt
	s_mov_b64 exec, s[0:1]
	s_add_u32 s24, s24, 0xe0
	s_cmpk_ge_u32 s25, 4480
	s_cbranch_scc1 .Ltc2_exit
	s_waitcnt vmcnt(15)
	v_add_u32_e32 v28, 16896, v22
	ds_write2_b32 v28, v58, v59 offset1:1
	ds_write2_b32 v28, v60, v61 offset0:2 offset1:3
	v_add_u32_e32 v28, 0x2080, v28
	ds_write2_b32 v28, v62, v63 offset1:1
	ds_write2_b32 v28, v64, v65 offset0:2 offset1:3
	s_mov_b32 s21, s25
	s_mov_b32 s0, s21
	s_cmpk_lt_u32 s0, 9600
	s_cbranch_scc0 .Ltc2_c260
	s_and_b32 s1, s0, 31
	s_lshl_b32 s1, s1, 6
	s_lshr_b32 s21, s0, 5
	s_lshl_b32 s21, s21, 17
	s_add_u32 s1, s1, s21
	s_lshl_b32 s1, s1, 1
	s_add_u32 s1, s1, 0x4001000
	s_add_u32 s30, s68, s1
	s_addc_u32 s31, s69, 0
	s_movk_i32 s20, 0x800
	s_branch .Ltc2_d259

; __device__ __forceinline__ unsigned cvt_pk_bf16(float lo, float hi) { unsigned r; asm("v_cvt_pk_bf16_f32 %0, %1, %2" : "=v"(r) : "v"(lo), "v"(hi)); return r; }
; __device__ __forceinline__ void tconv_tile(LAS float* tile, const float* src, int ld, int k0, int n0, int mode, bf16_t* dst, int K) {
;     ...
;     for (int it = 0; it < 2; ++it) { const int idx = tid + it * 512, kk = idx >> 4, n4 = (idx & 15) * 4, nn = n0 + n4; int oc = nn; bool valid = true;
;         if (mode == 1) { if (nn < 7680) oc = nn; else if (nn < 18944) oc = nn + 48; else if (nn < INW) oc = 7680 + (nn - 18944); else valid = false; }
;         f32x4 v = (f32x4){0.f, 0.f, 0.f, 0.f}; if (valid) v = *(const f32x4*)(src + (size_t)(k0 + kk) * ld + oc);
;         tile[kk * 65 + n4 + 0] = v[0]; tile[kk * 65 + n4 + 1] = v[1]; tile[kk * 65 + n4 + 2] = v[2]; tile[kk * 65 + n4 + 3] = v[3]; }
;     __syncthreads();
;     { const int n = tid >> 3, k8 = (tid & 7) * 8; float v[8];
; #pragma unroll
;         for (int e = 0; e < 8; ++e) v[e] = tile[(k8 + e) * 65 + n];
;         u32x4 w; w.x = cvt_pk_bf16(v[0], v[1]); w.y = cvt_pk_bf16(v[2], v[3]); w.z = cvt_pk_bf16(v[4], v[5]); w.w = cvt_pk_bf16(v[6], v[7]);
;         *(u32x4*)(dst + (size_t)(n0 + n) * K + k0 + k8) = w; }
; __device__ __forceinline__ void prologue(LAS unsigned char* lds, const Ctx& P, int l) {
;     ...
;     for (int t = blockIdx.x; t < T_ALL; t += G) {
;         int q = t;
;         if (q < T_IN) { const int kt = q & 31, ntl = q >> 5; tconv_tile(tile, P.in[3] + (size_t)l * DM * INW, INW, kt * 64, ntl * 64, 1, (bf16_t*)(ws + WS_WIN), DM); continue; }
.Ltc2_d266:
	v_mov_b32_e32 v58, 0
	v_mov_b32_e32 v59, 0
	v_mov_b32_e32 v60, 0
	v_mov_b32_e32 v61, 0
	v_mov_b32_e32 v62, 0
	v_mov_b32_e32 v63, 0
	v_mov_b32_e32 v64, 0
	v_mov_b32_e32 v65, 0
	v_mul_u32_u24_e32 v26, s28, v20
	v_add_lshl_u32 v26, v26, v21, 2
	s_lshl_b32 s0, s28, 7
	v_add_u32_e32 v27, s0, v26
	v_cmp_gt_i32_e32 vcc, s29, v21
	s_and_saveexec_b64 s[0:1], vcc
	global_load_dwordx4 v[58:61], v26, s[26:27] nt
	global_load_dwordx4 v[62:65], v27, s[26:27] nt
	s_mov_b64 exec, s[0:1]
	s_add_u32 s24, s24, 0xe0
	s_cmpk_ge_u32 s25, 4480
	s_cbranch_scc1 .Ltc2_exit
	s_waitcnt vmcnt(15)
	v_add_u32_e32 v28, 0, v22
	ds_write2_b32 v28, v78, v79 offset1:1
	ds_write2_b32 v28, v80, v81 offset0:2 offset1:3
	v_add_u32_e32 v28, 0x2080, v28
	ds_write2_b32 v28, v82, v83 offset1:1
	ds_write2_b32 v28, v84, v85 offset0:2 offset1:3
	s_mov_b32 s21, s25
	s_mov_b32 s0, s21
	s_cmpk_lt_u32 s0, 9600
	s_cbranch_scc0 .Ltc2_c280
	s_and_b32 s1, s0, 31
	s_lshl_b32 s1, s1, 6
	s_lshr_b32 s21, s0, 5
	s_lshl_b32 s21, s21, 17
	s_add_u32 s1, s1, s21
	s_lshl_b32 s1, s1, 1
	s_add_u32 s1, s1, 0x4001000
	s_add_u32 s30, s68, s1
	s_addc_u32 s31, s69, 0
	s_movk_i32 s20, 0x800
	s_branch .Ltc2_d279

; __device__ __forceinline__ void tconv_tile(LAS float* tile, const float* src, int ld, int k0, int n0, int mode, bf16_t* dst, int K) {
;     ...
;     for (int it = 0; it < 2; ++it) { const int idx = tid + it * 512, kk = idx >> 4, n4 = (idx & 15) * 4, nn = n0 + n4; int oc = nn; bool valid = true;
;         if (mode == 1) { if (nn < 7680) oc = nn; else if (nn < 18944) oc = nn + 48; else if (nn < INW) oc = 7680 + (nn - 18944); else valid = false; }
;         f32x4 v = (f32x4){0.f, 0.f, 0.f, 0.f}; if (valid) v = *(const f32x4*)(src + (size_t)(k0 + kk) * ld + oc);
; __device__ __forceinline__ void prologue(LAS unsigned char* lds, const Ctx& P, int l) {
;     ...
;     for (int t = blockIdx.x; t < T_ALL; t += G) {
;         int q = t;
;         if (q < T_IN) { const int kt = q & 31, ntl = q >> 5; tconv_tile(tile, P.in[3] + (size_t)l * DM * INW, INW, kt * 64, ntl * 64, 1, (bf16_t*)(ws + WS_WIN), DM); continue; }
.Ltc2_d306:
	v_mov_b32_e32 v86, 0
	v_mov_b32_e32 v87, 0
	v_mov_b32_e32 v88, 0
	v_mov_b32_e32 v89, 0
	v_mov_b32_e32 v90, 0
	v_mov_b32_e32 v91, 0
	v_mov_b32_e32 v92, 0
	v_mov_b32_e32 v93, 0
	v_mul_u32_u24_e32 v26, s28, v20
	v_add_lshl_u32 v26, v26, v21, 2
	s_lshl_b32 s0, s28, 7
	v_add_u32_e32 v27, s0, v26
	v_cmp_gt_i32_e32 vcc, s29, v21
	s_and_saveexec_b64 s[0:1], vcc
	global_load_dwordx4 v[86:89], v26, s[26:27] nt
	global_load_dwordx4 v[90:93], v27, s[26:27] nt
	s_mov_b64 exec, s[0:1]
	s_add_u32 s24, s24, 0xe0
	s_branch .Ltc2_loop
